# v066 plus QKV loop LOAD segments rewritten with SGPR-base LDS-DMA (no VALU address math), same as FFN-in
# speedup vs baseline: 1.0047x; 1.0047x over previous
.LBB0_491:
	s_add_u32 s18, s16, 0xfff80080
	s_addc_u32 s19, s17, -1
	s_cmp_eq_u32 s53, 28
	s_cselect_b32 s21, s11, s19
	s_cselect_b32 s20, s49, s18
	s_cselect_b32 s19, s9, s52
	s_cselect_b32 s18, s50, s51
	s_add_i32 s54, 0, 0x10000
	s_add_i32 s56, 0, 0x14000
	v_add_u32_e32 v208, 0x10000, v141
	ds_read_b128 v[144:147], v208
	ds_read_b128 v[148:151], v208 offset:1024
	ds_read_b128 v[152:155], v208 offset:2048
	ds_read_b128 v[156:159], v208 offset:3072
	ds_read_b128 v[160:163], v208 offset:16384
	ds_read_b128 v[164:167], v208 offset:17408
	ds_read_b128 v[168:171], v208 offset:18432
	ds_read_b128 v[172:175], v208 offset:19456
	s_add_i32 m0, s39, 0xc000
	ds_read_b128 v[176:179], v143
	ds_read_b128 v[180:183], v143 offset:1024
	ds_read_b128 v[184:187], v143 offset:2048
	ds_read_b128 v[188:191], v143 offset:3072
	ds_read_b128 v[192:195], v143 offset:4096
	ds_read_b128 v[196:199], v143 offset:5120
	ds_read_b128 v[200:203], v143 offset:6144
	ds_read_b128 v[204:207], v143 offset:7168
	global_load_lds_dwordx4 v136, s[16:17]
	s_add_i32 m0, s39, 0xe000
	s_nop 0
	global_load_lds_dwordx4 v138, s[16:17]
	s_waitcnt vmcnt(8)
	s_waitcnt lgkmcnt(0)
	s_setprio 1
	s_barrier
	v_mfma_f32_16x16x32_bf16 v[126:129], v[144:147], v[176:179], v[126:129]
	v_mfma_f32_16x16x32_bf16 v[122:125], v[152:155], v[176:179], v[122:125]
	v_mfma_f32_16x16x32_bf16 v[118:121], v[144:147], v[184:187], v[118:121]
	v_mfma_f32_16x16x32_bf16 v[114:117], v[152:155], v[184:187], v[114:117]
	v_mfma_f32_16x16x32_bf16 v[102:105], v[144:147], v[192:195], v[102:105]
	v_mfma_f32_16x16x32_bf16 v[98:101], v[152:155], v[192:195], v[98:101]
	v_mfma_f32_16x16x32_bf16 v[86:89], v[144:147], v[200:203], v[86:89]
	v_mfma_f32_16x16x32_bf16 v[82:85], v[152:155], v[200:203], v[82:85]
	v_mfma_f32_16x16x32_bf16 v[126:129], v[148:151], v[180:183], v[126:129]
	v_mfma_f32_16x16x32_bf16 v[122:125], v[156:159], v[180:183], v[122:125]
	v_mfma_f32_16x16x32_bf16 v[118:121], v[148:151], v[188:191], v[118:121]
	v_mfma_f32_16x16x32_bf16 v[114:117], v[156:159], v[188:191], v[114:117]
	v_mfma_f32_16x16x32_bf16 v[102:105], v[148:151], v[196:199], v[102:105]
	v_mfma_f32_16x16x32_bf16 v[98:101], v[156:159], v[196:199], v[98:101]
	v_mfma_f32_16x16x32_bf16 v[86:89], v[148:151], v[204:207], v[86:89]
	v_mfma_f32_16x16x32_bf16 v[82:85], v[156:159], v[204:207], v[82:85]
	s_setprio 0
	s_setprio 1
	v_mfma_f32_16x16x32_bf16 v[110:113], v[160:163], v[176:179], v[110:113]
	v_mfma_f32_16x16x32_bf16 v[106:109], v[168:171], v[176:179], v[106:109]
	v_mfma_f32_16x16x32_bf16 v[94:97], v[160:163], v[184:187], v[94:97]
	v_mfma_f32_16x16x32_bf16 v[90:93], v[168:171], v[184:187], v[90:93]
	v_mfma_f32_16x16x32_bf16 v[78:81], v[160:163], v[192:195], v[78:81]
	v_mfma_f32_16x16x32_bf16 v[74:77], v[168:171], v[192:195], v[74:77]
	v_mfma_f32_16x16x32_bf16 v[70:73], v[160:163], v[200:203], v[70:73]
	v_mfma_f32_16x16x32_bf16 v[66:69], v[168:171], v[200:203], v[66:69]
	v_mfma_f32_16x16x32_bf16 v[110:113], v[164:167], v[180:183], v[110:113]
	v_mfma_f32_16x16x32_bf16 v[106:109], v[172:175], v[180:183], v[106:109]
	v_mfma_f32_16x16x32_bf16 v[94:97], v[164:167], v[188:191], v[94:97]
	v_mfma_f32_16x16x32_bf16 v[90:93], v[172:175], v[188:191], v[90:93]
	v_mfma_f32_16x16x32_bf16 v[78:81], v[164:167], v[196:199], v[78:81]
	v_mfma_f32_16x16x32_bf16 v[74:77], v[172:175], v[196:199], v[74:77]
	v_mfma_f32_16x16x32_bf16 v[70:73], v[164:167], v[204:207], v[70:73]
	v_mfma_f32_16x16x32_bf16 v[66:69], v[172:175], v[204:207], v[66:69]
	s_barrier
	s_setprio 0
	s_add_i32 s54, s54, s37
	s_mov_b32 m0, s54
	ds_read_b128 v[176:179], v143 offset:16384
	ds_read_b128 v[180:183], v143 offset:17408
	ds_read_b128 v[184:187], v143 offset:18432
	ds_read_b128 v[188:191], v143 offset:19456
	ds_read_b128 v[192:195], v143 offset:20480
	ds_read_b128 v[196:199], v143 offset:21504
	ds_read_b128 v[200:203], v143 offset:22528
	ds_read_b128 v[204:207], v143 offset:23552
	global_load_lds_dwordx4 v0, s[18:19]
	s_add_i32 m0, s54, 0x2000
	s_add_u32 s54, s18, 0x80000
	s_addc_u32 s55, s19, 0
	s_add_i32 s56, s56, s37
	global_load_lds_dwordx4 v130, s[18:19]
	s_mov_b32 m0, s56
	s_nop 0
	global_load_lds_dwordx4 v0, s[54:55]
	s_add_i32 m0, s56, 0x2000
	s_nop 0
	global_load_lds_dwordx4 v130, s[54:55]
	s_mov_b32 m0, s39
	s_nop 0
	global_load_lds_dwordx4 v134, s[20:21]
	s_mov_b32 m0, s40
	s_nop 0
	global_load_lds_dwordx4 v132, s[20:21]
	s_waitcnt vmcnt(8)
	s_waitcnt lgkmcnt(0)
	s_setprio 1
	s_barrier
	v_mfma_f32_16x16x32_bf16 v[62:65], v[144:147], v[176:179], v[62:65]
	v_mfma_f32_16x16x32_bf16 v[58:61], v[152:155], v[176:179], v[58:61]
	v_mfma_f32_16x16x32_bf16 v[54:57], v[144:147], v[184:187], v[54:57]
	v_mfma_f32_16x16x32_bf16 v[50:53], v[152:155], v[184:187], v[50:53]
	v_mfma_f32_16x16x32_bf16 v[38:41], v[144:147], v[192:195], v[38:41]
	v_mfma_f32_16x16x32_bf16 v[34:37], v[152:155], v[192:195], v[34:37]
	v_mfma_f32_16x16x32_bf16 v[22:25], v[144:147], v[200:203], v[22:25]
	v_mfma_f32_16x16x32_bf16 v[18:21], v[152:155], v[200:203], v[18:21]
	v_mfma_f32_16x16x32_bf16 v[62:65], v[148:151], v[180:183], v[62:65]
	v_mfma_f32_16x16x32_bf16 v[58:61], v[156:159], v[180:183], v[58:61]
	v_mfma_f32_16x16x32_bf16 v[54:57], v[148:151], v[188:191], v[54:57]
	v_mfma_f32_16x16x32_bf16 v[50:53], v[156:159], v[188:191], v[50:53]
	v_mfma_f32_16x16x32_bf16 v[38:41], v[148:151], v[196:199], v[38:41]
	v_mfma_f32_16x16x32_bf16 v[34:37], v[156:159], v[196:199], v[34:37]
	v_mfma_f32_16x16x32_bf16 v[22:25], v[148:151], v[204:207], v[22:25]
	v_mfma_f32_16x16x32_bf16 v[18:21], v[156:159], v[204:207], v[18:21]
	s_setprio 0
	s_setprio 1
	v_mfma_f32_16x16x32_bf16 v[46:49], v[160:163], v[176:179], v[46:49]
	v_mfma_f32_16x16x32_bf16 v[42:45], v[168:171], v[176:179], v[42:45]
	v_mfma_f32_16x16x32_bf16 v[30:33], v[160:163], v[184:187], v[30:33]
	v_mfma_f32_16x16x32_bf16 v[26:29], v[168:171], v[184:187], v[26:29]
	v_mfma_f32_16x16x32_bf16 v[14:17], v[160:163], v[192:195], v[14:17]
	v_mfma_f32_16x16x32_bf16 v[10:13], v[168:171], v[192:195], v[10:13]
	v_mfma_f32_16x16x32_bf16 v[6:9], v[160:163], v[200:203], v[6:9]
	v_mfma_f32_16x16x32_bf16 v[2:5], v[168:171], v[200:203], v[2:5]
	v_mfma_f32_16x16x32_bf16 v[46:49], v[164:167], v[180:183], v[46:49]
	v_mfma_f32_16x16x32_bf16 v[42:45], v[172:175], v[180:183], v[42:45]
	v_mfma_f32_16x16x32_bf16 v[30:33], v[164:167], v[188:191], v[30:33]
	v_mfma_f32_16x16x32_bf16 v[26:29], v[172:175], v[188:191], v[26:29]
	v_mfma_f32_16x16x32_bf16 v[14:17], v[164:167], v[196:199], v[14:17]
	v_mfma_f32_16x16x32_bf16 v[10:13], v[172:175], v[196:199], v[10:13]
	v_mfma_f32_16x16x32_bf16 v[6:9], v[164:167], v[204:207], v[6:9]
	v_mfma_f32_16x16x32_bf16 v[2:5], v[172:175], v[204:207], v[2:5]
	s_barrier
	s_setprio 0
	ds_read_b128 v[144:147], v208 offset:32768
	ds_read_b128 v[148:151], v208 offset:33792
	ds_read_b128 v[152:155], v208 offset:34816
	ds_read_b128 v[156:159], v208 offset:35840
	ds_read_b128 v[160:163], v208 offset:49152
	ds_read_b128 v[164:167], v208 offset:50176
	ds_read_b128 v[168:171], v208 offset:51200
	ds_read_b128 v[172:175], v208 offset:52224
	s_add_i32 s54, 0, 0x18000
	s_add_i32 s55, 0, 0x1c000
	s_add_u32 s20, s20, 0x80000
	s_addc_u32 s21, s21, 0
	s_mov_b32 m0, s41
	ds_read_b128 v[176:179], v143 offset:32768
	ds_read_b128 v[180:183], v143 offset:33792
	ds_read_b128 v[184:187], v143 offset:34816
	ds_read_b128 v[188:191], v143 offset:35840
	ds_read_b128 v[192:195], v143 offset:36864
	ds_read_b128 v[196:199], v143 offset:37888
	ds_read_b128 v[200:203], v143 offset:38912
	ds_read_b128 v[204:207], v143 offset:39936
	global_load_lds_dwordx4 v134, s[20:21]
	s_mov_b32 m0, s44
	s_nop 0
	global_load_lds_dwordx4 v132, s[20:21]
	s_waitcnt vmcnt(8)
	s_waitcnt lgkmcnt(0)
	s_setprio 1
	s_barrier
	v_mfma_f32_16x16x32_bf16 v[126:129], v[144:147], v[176:179], v[126:129]
	v_mfma_f32_16x16x32_bf16 v[122:125], v[152:155], v[176:179], v[122:125]
	v_mfma_f32_16x16x32_bf16 v[118:121], v[144:147], v[184:187], v[118:121]
	v_mfma_f32_16x16x32_bf16 v[114:117], v[152:155], v[184:187], v[114:117]
	v_mfma_f32_16x16x32_bf16 v[102:105], v[144:147], v[192:195], v[102:105]
	v_mfma_f32_16x16x32_bf16 v[98:101], v[152:155], v[192:195], v[98:101]
	v_mfma_f32_16x16x32_bf16 v[86:89], v[144:147], v[200:203], v[86:89]
	v_mfma_f32_16x16x32_bf16 v[82:85], v[152:155], v[200:203], v[82:85]
	v_mfma_f32_16x16x32_bf16 v[126:129], v[148:151], v[180:183], v[126:129]
	v_mfma_f32_16x16x32_bf16 v[122:125], v[156:159], v[180:183], v[122:125]
	v_mfma_f32_16x16x32_bf16 v[118:121], v[148:151], v[188:191], v[118:121]
	v_mfma_f32_16x16x32_bf16 v[114:117], v[156:159], v[188:191], v[114:117]
	v_mfma_f32_16x16x32_bf16 v[102:105], v[148:151], v[196:199], v[102:105]
	v_mfma_f32_16x16x32_bf16 v[98:101], v[156:159], v[196:199], v[98:101]
	v_mfma_f32_16x16x32_bf16 v[86:89], v[148:151], v[204:207], v[86:89]
	v_mfma_f32_16x16x32_bf16 v[82:85], v[156:159], v[204:207], v[82:85]
	s_setprio 0
	s_setprio 1
	v_mfma_f32_16x16x32_bf16 v[110:113], v[160:163], v[176:179], v[110:113]
	v_mfma_f32_16x16x32_bf16 v[106:109], v[168:171], v[176:179], v[106:109]
	v_mfma_f32_16x16x32_bf16 v[94:97], v[160:163], v[184:187], v[94:97]
	v_mfma_f32_16x16x32_bf16 v[90:93], v[168:171], v[184:187], v[90:93]
	v_mfma_f32_16x16x32_bf16 v[78:81], v[160:163], v[192:195], v[78:81]
	v_mfma_f32_16x16x32_bf16 v[74:77], v[168:171], v[192:195], v[74:77]
	v_mfma_f32_16x16x32_bf16 v[70:73], v[160:163], v[200:203], v[70:73]
	v_mfma_f32_16x16x32_bf16 v[66:69], v[168:171], v[200:203], v[66:69]
	v_mfma_f32_16x16x32_bf16 v[110:113], v[164:167], v[180:183], v[110:113]
	v_mfma_f32_16x16x32_bf16 v[106:109], v[172:175], v[180:183], v[106:109]
	v_mfma_f32_16x16x32_bf16 v[94:97], v[164:167], v[188:191], v[94:97]
	v_mfma_f32_16x16x32_bf16 v[90:93], v[172:175], v[188:191], v[90:93]
	v_mfma_f32_16x16x32_bf16 v[78:81], v[164:167], v[196:199], v[78:81]
	v_mfma_f32_16x16x32_bf16 v[74:77], v[172:175], v[196:199], v[74:77]
	v_mfma_f32_16x16x32_bf16 v[70:73], v[164:167], v[204:207], v[70:73]
	v_mfma_f32_16x16x32_bf16 v[66:69], v[172:175], v[204:207], v[66:69]
	s_barrier
	s_setprio 0
	s_add_u32 vcc_lo, s20, 0xfff80080
	s_addc_u32 vcc_hi, s21, -1
	s_add_i32 s20, s54, s37
	s_add_i32 s56, s55, s37
	s_add_u32 s54, s18, 0x80
	s_addc_u32 s55, s19, 0
	s_add_u32 s18, s18, 0x80080
	s_addc_u32 s19, s19, 0
	s_mov_b32 m0, s20
	ds_read_b128 v[176:179], v143 offset:49152
	ds_read_b128 v[180:183], v143 offset:50176
	ds_read_b128 v[184:187], v143 offset:51200
	ds_read_b128 v[188:191], v143 offset:52224
	ds_read_b128 v[192:195], v143 offset:53248
	ds_read_b128 v[196:199], v143 offset:54272
	ds_read_b128 v[200:203], v143 offset:55296
	ds_read_b128 v[204:207], v143 offset:56320
	global_load_lds_dwordx4 v0, s[54:55]
	s_add_i32 m0, s20, 0x2000
	s_nop 0
	global_load_lds_dwordx4 v130, s[54:55]
	s_mov_b32 m0, s56
	s_nop 0
	global_load_lds_dwordx4 v0, s[18:19]
	s_add_i32 m0, s56, 0x2000
	s_nop 0
	global_load_lds_dwordx4 v130, s[18:19]
	s_mov_b32 m0, s45
	s_nop 0
	global_load_lds_dwordx4 v134, vcc
	s_mov_b32 m0, s46
	s_nop 0
	global_load_lds_dwordx4 v132, vcc
	s_waitcnt vmcnt(8)
	s_waitcnt lgkmcnt(0)
	s_setprio 1
	s_barrier
	v_mfma_f32_16x16x32_bf16 v[62:65], v[144:147], v[176:179], v[62:65]
	v_mfma_f32_16x16x32_bf16 v[58:61], v[152:155], v[176:179], v[58:61]
	v_mfma_f32_16x16x32_bf16 v[54:57], v[144:147], v[184:187], v[54:57]
	v_mfma_f32_16x16x32_bf16 v[50:53], v[152:155], v[184:187], v[50:53]
	v_mfma_f32_16x16x32_bf16 v[38:41], v[144:147], v[192:195], v[38:41]
	v_mfma_f32_16x16x32_bf16 v[34:37], v[152:155], v[192:195], v[34:37]
	v_mfma_f32_16x16x32_bf16 v[22:25], v[144:147], v[200:203], v[22:25]
	v_mfma_f32_16x16x32_bf16 v[18:21], v[152:155], v[200:203], v[18:21]
	v_mfma_f32_16x16x32_bf16 v[62:65], v[148:151], v[180:183], v[62:65]
	v_mfma_f32_16x16x32_bf16 v[58:61], v[156:159], v[180:183], v[58:61]
	v_mfma_f32_16x16x32_bf16 v[54:57], v[148:151], v[188:191], v[54:57]
	v_mfma_f32_16x16x32_bf16 v[50:53], v[156:159], v[188:191], v[50:53]
	v_mfma_f32_16x16x32_bf16 v[38:41], v[148:151], v[196:199], v[38:41]
	v_mfma_f32_16x16x32_bf16 v[34:37], v[156:159], v[196:199], v[34:37]
	v_mfma_f32_16x16x32_bf16 v[22:25], v[148:151], v[204:207], v[22:25]
	v_mfma_f32_16x16x32_bf16 v[18:21], v[156:159], v[204:207], v[18:21]
	s_setprio 0
	s_setprio 1
	v_mfma_f32_16x16x32_bf16 v[46:49], v[160:163], v[176:179], v[46:49]
	v_mfma_f32_16x16x32_bf16 v[42:45], v[168:171], v[176:179], v[42:45]
	v_mfma_f32_16x16x32_bf16 v[30:33], v[160:163], v[184:187], v[30:33]
	v_mfma_f32_16x16x32_bf16 v[26:29], v[168:171], v[184:187], v[26:29]
	v_mfma_f32_16x16x32_bf16 v[14:17], v[160:163], v[192:195], v[14:17]
	v_mfma_f32_16x16x32_bf16 v[10:13], v[168:171], v[192:195], v[10:13]
	v_mfma_f32_16x16x32_bf16 v[6:9], v[160:163], v[200:203], v[6:9]
	v_mfma_f32_16x16x32_bf16 v[2:5], v[168:171], v[200:203], v[2:5]
	v_mfma_f32_16x16x32_bf16 v[46:49], v[164:167], v[180:183], v[46:49]
	v_mfma_f32_16x16x32_bf16 v[42:45], v[172:175], v[180:183], v[42:45]
	v_mfma_f32_16x16x32_bf16 v[30:33], v[164:167], v[188:191], v[30:33]
	v_mfma_f32_16x16x32_bf16 v[26:29], v[172:175], v[188:191], v[26:29]
	v_mfma_f32_16x16x32_bf16 v[14:17], v[164:167], v[196:199], v[14:17]
	v_mfma_f32_16x16x32_bf16 v[10:13], v[172:175], v[196:199], v[10:13]
	v_mfma_f32_16x16x32_bf16 v[6:9], v[164:167], v[204:207], v[6:9]
	v_mfma_f32_16x16x32_bf16 v[2:5], v[172:175], v[204:207], v[2:5]
	s_barrier
	s_setprio 0
	s_add_i32 s53, s53, 2
	s_add_u32 s16, s16, 0x100
	s_addc_u32 s17, s17, 0
	s_add_u32 s51, s51, 0x100
	s_addc_u32 s52, s52, 0
	s_cmp_gt_u32 s53, 29
	s_cbranch_scc0 .LBB0_491
